# C pair tile: K fragments read in one burst with counted lgkm waits; V fragment ds_read_b64_tr issued in the QK MFMA shadow instead of after the softmax
# speedup vs baseline: 1.0091x; 1.0091x over previous
.LBB0_164:
	s_add_i32 s20, s6, -1
	s_cmp_le_i32 s20, s3
	s_cselect_b64 s[22:23], -1, 0
	s_cmp_gt_i32 s6, s19
	s_cselect_b64 s[24:25], -1, 0
	s_and_b64 s[22:23], s[22:23], s[24:25]
	s_andn2_b64 vcc, exec, s[22:23]
	s_cbranch_vccnz .LBB0_162
	s_and_b32 s21, s20, 3
	s_mul_i32 s7, s21, 0x2400
	v_add_u32_e32 v0, s7, v139
	ds_read_b128 v[208:211], v0
	ds_read_b128 v[212:215], v0 offset:4608
	ds_read_b128 v[216:219], v0 offset:32
	ds_read_b128 v[220:223], v0 offset:4640
	ds_read_b128 v[224:227], v0 offset:64
	ds_read_b128 v[228:231], v0 offset:4672
	ds_read_b128 v[232:235], v0 offset:96
	ds_read_b128 v[236:239], v0 offset:4704
	s_mul_i32 s22, s21, 0x3000
	v_add_u32_e32 v121, s22, v135
	s_cmp_lt_i32 s6, 33
	s_cselect_b64 s[6:7], -1, 0
	s_and_b64 vcc, exec, s[6:7]
	s_waitcnt lgkmcnt(7)
	v_mfma_f32_32x32x16_bf16 v[48:63], v[208:211], v[96:99], 0
	s_waitcnt lgkmcnt(6)
	v_mfma_f32_32x32x16_bf16 v[64:79], v[212:215], v[96:99], 0
	s_waitcnt lgkmcnt(5)
	v_mfma_f32_32x32x16_bf16 v[48:63], v[216:219], v[100:103], v[48:63]
	s_waitcnt lgkmcnt(4)
	v_mfma_f32_32x32x16_bf16 v[64:79], v[220:223], v[100:103], v[64:79]
	s_waitcnt lgkmcnt(3)
	v_mfma_f32_32x32x16_bf16 v[48:63], v[224:227], v[104:107], v[48:63]
	s_waitcnt lgkmcnt(2)
	v_mfma_f32_32x32x16_bf16 v[64:79], v[228:231], v[104:107], v[64:79]
	s_waitcnt lgkmcnt(1)
	v_mfma_f32_32x32x16_bf16 v[48:63], v[232:235], v[108:111], v[48:63]
	s_waitcnt lgkmcnt(0)
	v_mfma_f32_32x32x16_bf16 v[64:79], v[236:239], v[108:111], v[64:79]
	ds_read_b64_tr_b16 v[172:173], v121 offset:0
	ds_read_b64_tr_b16 v[174:175], v121 offset:1536
	ds_read_b64_tr_b16 v[168:169], v121 offset:64
	ds_read_b64_tr_b16 v[170:171], v121 offset:1600
	ds_read_b64_tr_b16 v[164:165], v121 offset:3072
	ds_read_b64_tr_b16 v[166:167], v121 offset:4608
	ds_read_b64_tr_b16 v[122:123], v121 offset:3136
	ds_read_b64_tr_b16 v[124:125], v121 offset:4672
	ds_read_b64_tr_b16 v[208:209], v121 offset:6144
	ds_read_b64_tr_b16 v[210:211], v121 offset:7680
	ds_read_b64_tr_b16 v[212:213], v121 offset:6208
	ds_read_b64_tr_b16 v[214:215], v121 offset:7744
	ds_read_b64_tr_b16 v[216:217], v121 offset:9216
	ds_read_b64_tr_b16 v[218:219], v121 offset:10752
	ds_read_b64_tr_b16 v[220:221], v121 offset:9280
	ds_read_b64_tr_b16 v[222:223], v121 offset:10816
	s_cbranch_vccnz .LBB0_167
	s_nop 10
	v_mov_b32_e32 v64, 0xff800000
	v_mov_b32_e32 v65, v64
	v_mov_b32_e32 v14, v64
	v_mov_b32_e32 v15, v64
	v_mov_b32_e32 v12, v64
	v_mov_b32_e32 v13, v64
	v_mov_b32_e32 v10, v64
	v_mov_b32_e32 v11, v64
	v_mov_b32_e32 v8, v64
	v_mov_b32_e32 v9, v64
	v_mov_b32_e32 v6, v64
	v_mov_b32_e32 v7, v64
	v_mov_b32_e32 v4, v64
	v_mov_b32_e32 v5, v64
	v_mov_b32_e32 v2, v64
	v_mov_b32_e32 v3, v64
	s_branch .LBB0_168

.LBB0_170:
	v_sub_f32_e32 v12, v12, v52
	v_exp_f32_e32 v61, v12
	v_sub_f32_e32 v12, v71, v52
	v_sub_f32_e32 v15, v15, v52
	v_exp_f32_e32 v60, v12
	v_sub_f32_e32 v12, v13, v52
	v_sub_f32_e32 v10, v10, v52
	v_sub_f32_e32 v8, v8, v52
	v_sub_f32_e32 v6, v6, v52
	v_sub_f32_e32 v4, v4, v52
	v_sub_f32_e32 v53, v77, v52
	v_sub_f32_e32 v54, v64, v52
	v_sub_f32_e32 v56, v65, v52
	v_exp_f32_e32 v59, v15
	v_sub_f32_e32 v15, v73, v52
	v_exp_f32_e32 v63, v12
	v_sub_f32_e32 v12, v69, v52
	v_exp_f32_e32 v65, v10
	v_sub_f32_e32 v10, v67, v52
	v_exp_f32_e32 v69, v8
	v_sub_f32_e32 v8, v68, v52
	v_exp_f32_e32 v73, v6
	v_sub_f32_e32 v6, v72, v52
	v_exp_f32_e32 v77, v4
	v_sub_f32_e32 v4, v50, v52
	v_sub_f32_e32 v2, v2, v52
	v_exp_f32_e32 v55, v54
	v_sub_f32_e32 v54, v76, v52
	v_sub_f32_e32 v14, v14, v52
	v_exp_f32_e32 v64, v10
	v_sub_f32_e32 v10, v11, v52
	v_exp_f32_e32 v68, v8
	v_sub_f32_e32 v8, v9, v52
	v_exp_f32_e32 v72, v6
	v_sub_f32_e32 v6, v7, v52
	v_exp_f32_e32 v76, v4
	v_sub_f32_e32 v4, v5, v52
	v_exp_f32_e32 v119, v2
	v_sub_f32_e32 v2, v48, v52
	v_exp_f32_e32 v57, v56
	v_sub_f32_e32 v56, v75, v52
	v_exp_f32_e32 v58, v14
	v_sub_f32_e32 v14, v74, v52
	v_exp_f32_e32 v67, v10
	v_sub_f32_e32 v10, v66, v52
	v_exp_f32_e32 v71, v8
	v_sub_f32_e32 v8, v70, v52
	v_exp_f32_e32 v75, v6
	v_sub_f32_e32 v6, v51, v52
	v_exp_f32_e32 v79, v4
	v_sub_f32_e32 v4, v49, v52
	v_exp_f32_e32 v118, v2
	v_sub_f32_e32 v2, v3, v52
	s_mulk_i32 s21, 0x3000
	v_exp_f32_e32 v53, v53
	v_exp_f32_e32 v54, v54
	v_exp_f32_e32 v56, v56
	v_exp_f32_e32 v14, v14
	v_exp_f32_e32 v15, v15
	v_exp_f32_e32 v62, v12
	v_exp_f32_e32 v66, v10
	v_exp_f32_e32 v70, v8
	v_exp_f32_e32 v74, v6
	v_exp_f32_e32 v78, v4
	v_exp_f32_e32 v120, v2
	s_waitcnt lgkmcnt(0)
	v_cvt_pk_bf16_f32 v176, v53, v54
	v_cvt_pk_bf16_f32 v177, v56, v14
	v_cvt_pk_bf16_f32 v178, v15, v60
	v_cvt_pk_bf16_f32 v179, v62, v64
	s_andn2_b64 vcc, exec, s[6:7]
	v_mfma_f32_32x32x16_bf16 v[32:47], v[172:175], v[176:179], v[32:47]
	v_mfma_f32_32x32x16_bf16 v[16:31], v[168:171], v[176:179], v[16:31]
	v_cvt_pk_bf16_f32 v168, v66, v68
	v_cvt_pk_bf16_f32 v169, v70, v72
	v_cvt_pk_bf16_f32 v170, v74, v76
	v_cvt_pk_bf16_f32 v171, v78, v118
	s_nop 0
	v_mfma_f32_32x32x16_bf16 v[32:47], v[164:167], v[168:171], v[32:47]
	v_mfma_f32_32x32x16_bf16 v[16:31], v[122:125], v[168:171], v[16:31]
	s_cbranch_vccnz .LBB0_172
	v_cvt_pk_bf16_f32 v122, v55, v57
	v_cvt_pk_bf16_f32 v123, v58, v59
	v_cvt_pk_bf16_f32 v124, v61, v63
	v_cvt_pk_bf16_f32 v125, v65, v67
	s_nop 0
	v_mfma_f32_32x32x16_bf16 v[32:47], v[208:211], v[122:125], v[32:47]
	v_mfma_f32_32x32x16_bf16 v[16:31], v[212:215], v[122:125], v[16:31]
	v_cvt_pk_bf16_f32 v10, v69, v71
	v_cvt_pk_bf16_f32 v11, v73, v75
	v_cvt_pk_bf16_f32 v12, v77, v79
	v_cvt_pk_bf16_f32 v13, v119, v120
	s_nop 0
	v_mfma_f32_32x32x16_bf16 v[32:47], v[216:219], v[10:13], v[32:47]
	v_mfma_f32_32x32x16_bf16 v[16:31], v[220:223], v[10:13], v[16:31]
